# v62 + up GEMM: last epilogue row group (accumulators v0-15) deferred into the next unit's first compute segment, interleaved between its MFMAs (MFMA shadow); last unit of a phase runs it inline
# baseline (speedup 1.0000x reference)
.LBB0_174:
	v_and_b32_e32 v144, 15, v10
	v_lshrrev_b32_e32 v10, 1, v10
	v_readlane_b32 s62, v254, 6
	v_and_b32_e32 v10, 24, v10
	s_lshl_b32 s18, s18, 5
	v_mov_b32_e32 v133, v153
	v_readlane_b32 s63, v254, 7
	v_lshlrev_b32_e32 v11, 1, v10
	v_lshlrev_b32_e32 v16, 2, v144
	s_and_b32 s21, s18, 0x60
	s_add_i32 m0, s68, 0x18000
	v_lshl_add_u64 v[0:1], v[0:1], 0, s[22:23]
	v_lshl_add_u64 v[12:13], s[62:63], 0, v[132:133]
	v_mov_b32_e32 v131, v153
	s_lshl_b32 s76, s19, 6
	v_lshl_or_b32 v11, v144, 6, v11
	s_lshl_b32 s19, s19, 13
	v_and_b32_e32 v17, 32, v16
	s_lshl_b32 s18, s21, 7
	s_waitcnt vmcnt(2)
	s_barrier
	global_load_lds_dwordx4 v[0:1], off
	v_lshl_add_u64 v[0:1], v[2:3], 0, s[22:23]
	s_add_i32 m0, s68, 0x1a000
	s_add_i32 s77, s68, 0x8000
	s_add_i32 s78, s68, 0xa000
	v_lshl_add_u64 v[14:15], s[62:63], 0, v[130:131]
	v_bitop3_b32 v145, v11, s18, v17 bitop3:0xde
	global_load_lds_dwordx4 v[0:1], off
	v_lshl_add_u64 v[0:1], v[12:13], 0, s[22:23]
	s_mov_b32 m0, s77
	s_add_u32 s18, s60, 0x40080
	v_bitop3_b32 v18, v11, s19, v17 bitop3:0xde
	global_load_lds_dwordx4 v[0:1], off
	v_lshl_add_u64 v[0:1], v[14:15], 0, s[22:23]
	s_mov_b32 m0, s78
	s_addc_u32 s19, s61, 0
	global_load_lds_dwordx4 v[0:1], off
	s_add_i32 m0, s68, 0x1c000
	v_lshl_add_u64 v[0:1], s[18:19], 0, v[152:153]
	global_load_lds_dwordx4 v[0:1], off
	v_lshl_add_u64 v[0:1], s[18:19], 0, v[128:129]
	s_add_i32 m0, s68, 0x1e000
	s_cmpk_lt_u32 s20, 0x100
	global_load_lds_dwordx4 v[0:1], off
	v_lshlrev_b32_e32 v0, 14, v4
	v_and_b32_e32 v0, 0xffff8000, v0
	v_lshl_add_u32 v0, v5, 11, v0
	v_and_b32_e32 v1, 1, v4
	v_lshl_or_b32 v0, v1, 6, v0
	s_cselect_b64 s[18:19], -1, 0
	s_and_b32 s20, s20, 0xffffff00
	v_lshl_add_u32 v134, v6, 1, v0
	v_lshlrev_b32_e32 v0, 14, v8
	s_add_i32 s20, s20, 0
	v_and_b32_e32 v0, 0xffff8000, v0
	s_waitcnt vmcnt(6)
	s_add_i32 s20, s20, 0x20400
	v_lshl_add_u32 v0, v7, 11, v0
	v_and_b32_e32 v1, 1, v8
	v_add_u32_e32 v146, s20, v16
	v_or_b32_e32 v147, s21, v10
	v_lshl_or_b32 v0, v1, 6, v0
	v_readlane_b32 s20, v253, 16
	v_mov_b32_e32 v135, v153
	v_lshl_add_u32 v136, v9, 1, v0
	v_mov_b32_e32 v137, v153
	s_mov_b32 s79, 0
	v_add_u32_e32 v148, 0, v18
	v_readlane_b32 s80, v253, 15
	s_mov_b32 s81, s20
	s_barrier
	v_readlane_b32 s21, v253, 17
	s_mov_b32 s32, 0
	s_branch .LBB0_177

.LBB0_176:
	s_andn2_b64 vcc, exec, s[44:45]
	s_mov_b32 s80, s20
	s_mov_b32 s81, s46
	s_mov_b64 s[60:61], s[50:51]
	s_mov_b64 s[62:63], s[48:49]
	s_cbranch_vccz .LBB0_186
	s_mov_b32 s32, 1
	s_bitcmp1_b32 s18, 0
	s_cbranch_scc1 .Lmy_up_h2

.LBB0_179:
	s_ashr_i32 s47, s46, 31
	s_lshl_b64 s[48:49], s[46:47], 19
	s_add_u32 s48, s26, s48
	s_addc_u32 s49, s27, s49
	s_and_b64 s[50:51], s[44:45], exec
	s_cselect_b32 s47, s49, s63
	s_cselect_b32 s82, s48, s62
	s_ashr_i32 s21, s20, 31
	s_lshl_b64 s[50:51], s[20:21], 19
	s_add_u32 s50, s59, s50
	s_addc_u32 s51, s66, s51
	s_and_b64 s[84:85], s[44:45], exec
	s_cselect_b32 s21, s51, s61
	s_cselect_b32 s83, s50, s60
	s_add_u32 s89, s60, 0x100
	s_addc_u32 s84, s61, 0
	s_add_u32 s60, s62, 0x40080
	s_addc_u32 s61, s63, 0
	s_mov_b32 s85, -2
	s_add_u32 s62, s60, 0xfffc0080
	s_addc_u32 s63, s61, -1
	s_cmp_eq_u32 s85, 12
	s_cselect_b32 vcc_hi, s47, s63
	s_cselect_b32 vcc_lo, s82, s62
	s_cselect_b32 s63, s21, s84
	s_cselect_b32 s62, s83, s89
	v_lshl_add_u64 v[142:143], s[60:61], 0, v[136:137]
	s_add_i32 m0, s68, 0xc000
	global_load_lds_dwordx4 v[142:143], off
	v_lshl_add_u64 v[142:143], s[60:61], 0, v[134:135]
	s_add_i32 m0, s68, 0xe000
	s_nop 0
	global_load_lds_dwordx4 v[142:143], off
	s_waitcnt vmcnt(8)
	s_waitcnt lgkmcnt(0)
	s_cmp_eq_u32 s32, 1
	s_cbranch_scc0 .Lmy_up_norm
	s_barrier
	s_setprio 1
	s_waitcnt lgkmcnt(0)
	v_mfma_f32_16x16x32_bf16 v[124:127], v[138:141], v[210:213], 0
	v_mul_f32_e32 v22, 0xbfb8aa3b, v30
	v_pk_mul_f32 v[24:25], v[14:15], v[22:23] op_sel_hi:[1,0]
	v_mfma_f32_16x16x32_bf16 v[116:119], v[176:179], v[210:213], 0
	v_pk_mul_f32 v[26:27], v[12:13], v[22:23] op_sel_hi:[1,0]
	v_mfma_f32_16x16x32_bf16 v[108:111], v[138:141], v[218:221], 0
	v_exp_f32_e32 v24, v24
	v_exp_f32_e32 v26, v26
	v_mfma_f32_16x16x32_bf16 v[100:103], v[176:179], v[218:221], 0
	v_exp_f32_e32 v25, v25
	v_mfma_f32_16x16x32_bf16 v[92:95], v[138:141], v[228:231], 0
	v_exp_f32_e32 v27, v27
	s_nop 0
	v_pk_add_f32 v[20:21], v[26:27], 1.0 op_sel_hi:[1,0]
	v_mfma_f32_16x16x32_bf16 v[84:87], v[176:179], v[228:231], 0
	v_pk_mul_f32 v[10:11], v[14:15], v[10:11]
	v_mfma_f32_16x16x32_bf16 v[76:79], v[138:141], v[236:239], 0
	v_pk_add_f32 v[18:19], v[24:25], 1.0 op_sel_hi:[1,0]
	v_rcp_f32_e32 v20, v20
	v_mfma_f32_16x16x32_bf16 v[68:71], v[176:179], v[236:239], 0
	v_rcp_f32_e32 v18, v18
	v_mfma_f32_16x16x32_bf16 v[124:127], v[172:175], v[214:217], v[124:127]
	v_rcp_f32_e32 v19, v19
	v_rcp_f32_e32 v21, v21
	v_mfma_f32_16x16x32_bf16 v[116:119], v[180:183], v[214:217], v[116:119]
	v_mul_f32_e32 v16, v30, v30
	v_mfma_f32_16x16x32_bf16 v[108:111], v[172:175], v[224:227], v[108:111]
	v_pk_mul_f32 v[8:9], v[12:13], v[8:9]
	v_pk_mul_f32 v[12:13], v[16:17], v[18:19] op_sel_hi:[0,1]
	v_mfma_f32_16x16x32_bf16 v[100:103], v[180:183], v[224:227], v[100:103]
	v_pk_mul_f32 v[14:15], v[16:17], v[20:21] op_sel_hi:[0,1]
	v_mfma_f32_16x16x32_bf16 v[92:95], v[172:175], v[232:235], v[92:95]
	v_pk_mul_f32 v[18:19], v[6:7], v[22:23] op_sel_hi:[1,0]
	v_pk_mul_f32 v[20:21], v[4:5], v[22:23] op_sel_hi:[1,0]
	v_mfma_f32_16x16x32_bf16 v[84:87], v[180:183], v[232:235], v[84:87]
	v_exp_f32_e32 v18, v18
	v_mfma_f32_16x16x32_bf16 v[76:79], v[172:175], v[240:243], v[76:79]
	v_exp_f32_e32 v20, v20
	v_exp_f32_e32 v19, v19
	v_mfma_f32_16x16x32_bf16 v[68:71], v[180:183], v[240:243], v[68:71]
	v_exp_f32_e32 v21, v21
	s_setprio 0
	s_setprio 1
	v_mfma_f32_16x16x32_bf16 v[120:123], v[184:187], v[210:213], 0
	v_pk_mul_f32 v[10:11], v[10:11], v[12:13]
	v_pk_mul_f32 v[8:9], v[8:9], v[14:15]
	v_mfma_f32_16x16x32_bf16 v[112:115], v[192:195], v[210:213], 0
	v_pk_add_f32 v[12:13], v[18:19], 1.0 op_sel_hi:[1,0]
	v_mfma_f32_16x16x32_bf16 v[104:107], v[184:187], v[218:221], 0
	v_pk_add_f32 v[14:15], v[20:21], 1.0 op_sel_hi:[1,0]
	v_rcp_f32_e32 v12, v12
	v_mfma_f32_16x16x32_bf16 v[96:99], v[192:195], v[218:221], 0
	v_rcp_f32_e32 v14, v14
	v_mfma_f32_16x16x32_bf16 v[88:91], v[184:187], v[228:231], 0
	v_rcp_f32_e32 v13, v13
	v_rcp_f32_e32 v15, v15
	v_mfma_f32_16x16x32_bf16 v[80:83], v[192:195], v[228:231], 0
	v_pk_mul_f32 v[2:3], v[6:7], v[2:3]
	v_mfma_f32_16x16x32_bf16 v[72:75], v[184:187], v[236:239], 0
	v_pk_mul_f32 v[0:1], v[4:5], v[0:1]
	v_pk_mul_f32 v[4:5], v[16:17], v[12:13] op_sel_hi:[0,1]
	v_mfma_f32_16x16x32_bf16 v[64:67], v[192:195], v[236:239], 0
	v_pk_mul_f32 v[6:7], v[16:17], v[14:15] op_sel_hi:[0,1]
	v_mfma_f32_16x16x32_bf16 v[120:123], v[188:191], v[214:217], v[120:123]
	v_pk_mul_f32 v[4:5], v[2:3], v[4:5]
	v_pk_mul_f32 v[2:3], v[0:1], v[6:7]
	v_mfma_f32_16x16x32_bf16 v[112:115], v[196:199], v[214:217], v[112:115]
	v_cvt_pk_bf16_f32 v0, v8, v9
	v_mfma_f32_16x16x32_bf16 v[104:107], v[188:191], v[224:227], v[104:107]
	v_cvt_pk_bf16_f32 v1, v10, v11
	v_cvt_pk_bf16_f32 v2, v2, v3
	v_mfma_f32_16x16x32_bf16 v[96:99], v[196:199], v[224:227], v[96:99]
	v_cvt_pk_bf16_f32 v3, v4, v5
	v_mfma_f32_16x16x32_bf16 v[88:91], v[188:191], v[232:235], v[88:91]
	v_mfma_f32_16x16x32_bf16 v[80:83], v[196:199], v[232:235], v[80:83]
	v_mfma_f32_16x16x32_bf16 v[72:75], v[188:191], v[240:243], v[72:75]
	v_mfma_f32_16x16x32_bf16 v[64:67], v[196:199], v[240:243], v[64:67]
	global_store_dwordx4 v[28:29], v[0:3], off
	s_setprio 0
	s_barrier
	s_add_i32 s86, s86, s67
	v_lshl_add_u64 v[142:143], s[62:63], 0, v[152:153]
	s_mov_b32 m0, s86
	ds_read_b128 v[210:213], v148 offset:16384
	ds_read_b128 v[214:217], v148 offset:17408
	ds_read_b128 v[218:221], v148 offset:18432
	ds_read_b128 v[224:227], v148 offset:19456
	ds_read_b128 v[228:231], v148 offset:20480
	ds_read_b128 v[232:235], v148 offset:21504
	ds_read_b128 v[236:239], v148 offset:22528
	ds_read_b128 v[240:243], v148 offset:23552
	global_load_lds_dwordx4 v[142:143], off
	s_add_i32 m0, s86, 0x2000
	s_add_u32 s86, s62, 0x40000
	v_lshl_add_u64 v[150:151], s[62:63], 0, v[128:129]
	s_addc_u32 s87, s63, 0
	s_add_i32 s92, s92, s67
	global_load_lds_dwordx4 v[150:151], off
	v_lshl_add_u64 v[244:245], s[86:87], 0, v[152:153]
	s_mov_b32 m0, s92
	v_lshl_add_u64 v[246:247], vcc, 0, v[130:131]
	global_load_lds_dwordx4 v[244:245], off
	v_lshl_add_u64 v[244:245], s[86:87], 0, v[128:129]
	s_add_i32 m0, s92, 0x2000
	s_nop 0
	global_load_lds_dwordx4 v[244:245], off
	v_lshl_add_u64 v[244:245], vcc, 0, v[132:133]
	s_mov_b32 m0, s68
	s_nop 0
	global_load_lds_dwordx4 v[244:245], off
	s_mov_b32 m0, s69
	s_nop 0
	global_load_lds_dwordx4 v[246:247], off
	s_waitcnt vmcnt(9)
	s_branch .Lmy_up_join
.Lmy_up_norm:
	s_barrier
	s_setprio 1
	s_waitcnt lgkmcnt(0)
	v_mfma_f32_16x16x32_bf16 v[124:127], v[138:141], v[210:213], 0
	v_mfma_f32_16x16x32_bf16 v[116:119], v[176:179], v[210:213], 0
	v_mfma_f32_16x16x32_bf16 v[108:111], v[138:141], v[218:221], 0
	v_mfma_f32_16x16x32_bf16 v[100:103], v[176:179], v[218:221], 0
	v_mfma_f32_16x16x32_bf16 v[92:95], v[138:141], v[228:231], 0
	v_mfma_f32_16x16x32_bf16 v[84:87], v[176:179], v[228:231], 0
	v_mfma_f32_16x16x32_bf16 v[76:79], v[138:141], v[236:239], 0
	v_mfma_f32_16x16x32_bf16 v[68:71], v[176:179], v[236:239], 0
	v_mfma_f32_16x16x32_bf16 v[124:127], v[172:175], v[214:217], v[124:127]
	v_mfma_f32_16x16x32_bf16 v[116:119], v[180:183], v[214:217], v[116:119]
	v_mfma_f32_16x16x32_bf16 v[108:111], v[172:175], v[224:227], v[108:111]
	v_mfma_f32_16x16x32_bf16 v[100:103], v[180:183], v[224:227], v[100:103]
	v_mfma_f32_16x16x32_bf16 v[92:95], v[172:175], v[232:235], v[92:95]
	v_mfma_f32_16x16x32_bf16 v[84:87], v[180:183], v[232:235], v[84:87]
	v_mfma_f32_16x16x32_bf16 v[76:79], v[172:175], v[240:243], v[76:79]
	v_mfma_f32_16x16x32_bf16 v[68:71], v[180:183], v[240:243], v[68:71]
	s_setprio 0
	s_setprio 1
	v_mfma_f32_16x16x32_bf16 v[120:123], v[184:187], v[210:213], 0
	v_mfma_f32_16x16x32_bf16 v[112:115], v[192:195], v[210:213], 0
	v_mfma_f32_16x16x32_bf16 v[104:107], v[184:187], v[218:221], 0
	v_mfma_f32_16x16x32_bf16 v[96:99], v[192:195], v[218:221], 0
	v_mfma_f32_16x16x32_bf16 v[88:91], v[184:187], v[228:231], 0
	v_mfma_f32_16x16x32_bf16 v[80:83], v[192:195], v[228:231], 0
	v_mfma_f32_16x16x32_bf16 v[72:75], v[184:187], v[236:239], 0
	v_mfma_f32_16x16x32_bf16 v[64:67], v[192:195], v[236:239], 0
	v_mfma_f32_16x16x32_bf16 v[120:123], v[188:191], v[214:217], v[120:123]
	v_mfma_f32_16x16x32_bf16 v[112:115], v[196:199], v[214:217], v[112:115]
	v_mfma_f32_16x16x32_bf16 v[104:107], v[188:191], v[224:227], v[104:107]
	v_mfma_f32_16x16x32_bf16 v[96:99], v[196:199], v[224:227], v[96:99]
	v_mfma_f32_16x16x32_bf16 v[88:91], v[188:191], v[232:235], v[88:91]
	v_mfma_f32_16x16x32_bf16 v[80:83], v[196:199], v[232:235], v[80:83]
	v_mfma_f32_16x16x32_bf16 v[72:75], v[188:191], v[240:243], v[72:75]
	v_mfma_f32_16x16x32_bf16 v[64:67], v[196:199], v[240:243], v[64:67]
	s_setprio 0
	s_barrier
	s_add_i32 s86, s86, s67
	v_lshl_add_u64 v[142:143], s[62:63], 0, v[152:153]
	s_mov_b32 m0, s86
	ds_read_b128 v[210:213], v148 offset:16384
	ds_read_b128 v[214:217], v148 offset:17408
	ds_read_b128 v[218:221], v148 offset:18432
	ds_read_b128 v[224:227], v148 offset:19456
	ds_read_b128 v[228:231], v148 offset:20480
	ds_read_b128 v[232:235], v148 offset:21504
	ds_read_b128 v[236:239], v148 offset:22528
	ds_read_b128 v[240:243], v148 offset:23552
	global_load_lds_dwordx4 v[142:143], off
	s_add_i32 m0, s86, 0x2000
	s_add_u32 s86, s62, 0x40000
	v_lshl_add_u64 v[150:151], s[62:63], 0, v[128:129]
	s_addc_u32 s87, s63, 0
	s_add_i32 s92, s92, s67
	global_load_lds_dwordx4 v[150:151], off
	v_lshl_add_u64 v[244:245], s[86:87], 0, v[152:153]
	s_mov_b32 m0, s92
	v_lshl_add_u64 v[246:247], vcc, 0, v[130:131]
	global_load_lds_dwordx4 v[244:245], off
	v_lshl_add_u64 v[244:245], s[86:87], 0, v[128:129]
	s_add_i32 m0, s92, 0x2000
	s_nop 0
	global_load_lds_dwordx4 v[244:245], off
	v_lshl_add_u64 v[244:245], vcc, 0, v[132:133]
	s_mov_b32 m0, s68
	s_nop 0
	global_load_lds_dwordx4 v[244:245], off
	s_mov_b32 m0, s69
	s_nop 0
	global_load_lds_dwordx4 v[246:247], off
	s_waitcnt vmcnt(8)
.Lmy_up_join:
	s_waitcnt lgkmcnt(0)
	s_barrier
	s_setprio 1
	s_waitcnt lgkmcnt(0)
	v_mfma_f32_16x16x32_bf16 v[60:63], v[138:141], v[210:213], 0
	v_mfma_f32_16x16x32_bf16 v[52:55], v[176:179], v[210:213], 0
	v_mfma_f32_16x16x32_bf16 v[44:47], v[138:141], v[218:221], 0
	v_mfma_f32_16x16x32_bf16 v[36:39], v[176:179], v[218:221], 0
	v_mfma_f32_16x16x32_bf16 v[28:31], v[138:141], v[228:231], 0
	v_mfma_f32_16x16x32_bf16 v[20:23], v[176:179], v[228:231], 0
	v_mfma_f32_16x16x32_bf16 v[12:15], v[138:141], v[236:239], 0
	v_mfma_f32_16x16x32_bf16 v[4:7], v[176:179], v[236:239], 0
	v_mfma_f32_16x16x32_bf16 v[60:63], v[172:175], v[214:217], v[60:63]
	v_mfma_f32_16x16x32_bf16 v[52:55], v[180:183], v[214:217], v[52:55]
	v_mfma_f32_16x16x32_bf16 v[44:47], v[172:175], v[224:227], v[44:47]
	v_mfma_f32_16x16x32_bf16 v[36:39], v[180:183], v[224:227], v[36:39]
	v_mfma_f32_16x16x32_bf16 v[28:31], v[172:175], v[232:235], v[28:31]
	v_mfma_f32_16x16x32_bf16 v[20:23], v[180:183], v[232:235], v[20:23]
	v_mfma_f32_16x16x32_bf16 v[12:15], v[172:175], v[240:243], v[12:15]
	v_mfma_f32_16x16x32_bf16 v[4:7], v[180:183], v[240:243], v[4:7]
	s_setprio 0
	s_setprio 1
	v_mfma_f32_16x16x32_bf16 v[56:59], v[184:187], v[210:213], 0
	v_mfma_f32_16x16x32_bf16 v[48:51], v[192:195], v[210:213], 0
	v_mfma_f32_16x16x32_bf16 v[40:43], v[184:187], v[218:221], 0
	v_mfma_f32_16x16x32_bf16 v[32:35], v[192:195], v[218:221], 0
	v_mfma_f32_16x16x32_bf16 v[24:27], v[184:187], v[228:231], 0
	v_mfma_f32_16x16x32_bf16 v[16:19], v[192:195], v[228:231], 0
	v_mfma_f32_16x16x32_bf16 v[8:11], v[184:187], v[236:239], 0
	v_mfma_f32_16x16x32_bf16 v[0:3], v[192:195], v[236:239], 0
	v_mfma_f32_16x16x32_bf16 v[56:59], v[188:191], v[214:217], v[56:59]
	v_mfma_f32_16x16x32_bf16 v[48:51], v[196:199], v[214:217], v[48:51]
	v_mfma_f32_16x16x32_bf16 v[40:43], v[188:191], v[224:227], v[40:43]
	v_mfma_f32_16x16x32_bf16 v[32:35], v[196:199], v[224:227], v[32:35]
	v_mfma_f32_16x16x32_bf16 v[24:27], v[188:191], v[232:235], v[24:27]
	v_mfma_f32_16x16x32_bf16 v[16:19], v[196:199], v[232:235], v[16:19]
	v_mfma_f32_16x16x32_bf16 v[8:11], v[188:191], v[240:243], v[8:11]
	v_mfma_f32_16x16x32_bf16 v[0:3], v[196:199], v[240:243], v[0:3]
	s_setprio 0
	s_barrier
	s_add_i32 s92, 0, 0x18000
	v_add_u32_e32 v149, s92, v145
	s_add_i32 s93, 0, 0x1c000
	ds_read_b128 v[138:141], v149
	ds_read_b128 v[172:175], v149 offset:1024
	ds_read_b128 v[176:179], v149 offset:2048
	ds_read_b128 v[180:183], v149 offset:3072
	v_add_u32_e32 v149, s93, v145
	ds_read_b128 v[184:187], v149
	ds_read_b128 v[188:191], v149 offset:1024
	ds_read_b128 v[192:195], v149 offset:2048
	ds_read_b128 v[196:199], v149 offset:3072
	s_add_u32 s86, vcc_lo, 0x40000
	s_addc_u32 s87, vcc_hi, 0
	s_mov_b32 m0, s74
	v_lshl_add_u64 v[248:249], s[86:87], 0, v[132:133]
	ds_read_b128 v[210:213], v148 offset:32768
	ds_read_b128 v[214:217], v148 offset:33792
	ds_read_b128 v[218:221], v148 offset:34816
	ds_read_b128 v[224:227], v148 offset:35840
	ds_read_b128 v[228:231], v148 offset:36864
	ds_read_b128 v[232:235], v148 offset:37888
	ds_read_b128 v[236:239], v148 offset:38912
	ds_read_b128 v[240:243], v148 offset:39936
	global_load_lds_dwordx4 v[248:249], off
	v_lshl_add_u64 v[248:249], s[86:87], 0, v[130:131]
	s_mov_b32 m0, s75
	s_nop 0
	global_load_lds_dwordx4 v[248:249], off
	s_waitcnt vmcnt(8)
	s_waitcnt lgkmcnt(0)
	s_barrier
	s_setprio 1
	s_waitcnt lgkmcnt(0)
	v_mfma_f32_16x16x32_bf16 v[124:127], v[138:141], v[210:213], v[124:127]
	v_mfma_f32_16x16x32_bf16 v[116:119], v[176:179], v[210:213], v[116:119]
	v_mfma_f32_16x16x32_bf16 v[108:111], v[138:141], v[218:221], v[108:111]
	v_mfma_f32_16x16x32_bf16 v[100:103], v[176:179], v[218:221], v[100:103]
	v_mfma_f32_16x16x32_bf16 v[92:95], v[138:141], v[228:231], v[92:95]
	v_mfma_f32_16x16x32_bf16 v[84:87], v[176:179], v[228:231], v[84:87]
	v_mfma_f32_16x16x32_bf16 v[76:79], v[138:141], v[236:239], v[76:79]
	v_mfma_f32_16x16x32_bf16 v[68:71], v[176:179], v[236:239], v[68:71]
	v_mfma_f32_16x16x32_bf16 v[124:127], v[172:175], v[214:217], v[124:127]
	v_mfma_f32_16x16x32_bf16 v[116:119], v[180:183], v[214:217], v[116:119]
	v_mfma_f32_16x16x32_bf16 v[108:111], v[172:175], v[224:227], v[108:111]
	v_mfma_f32_16x16x32_bf16 v[100:103], v[180:183], v[224:227], v[100:103]
	v_mfma_f32_16x16x32_bf16 v[92:95], v[172:175], v[232:235], v[92:95]
	v_mfma_f32_16x16x32_bf16 v[84:87], v[180:183], v[232:235], v[84:87]
	v_mfma_f32_16x16x32_bf16 v[76:79], v[172:175], v[240:243], v[76:79]
	v_mfma_f32_16x16x32_bf16 v[68:71], v[180:183], v[240:243], v[68:71]
	s_setprio 0
	s_setprio 1
	v_mfma_f32_16x16x32_bf16 v[120:123], v[184:187], v[210:213], v[120:123]
	v_mfma_f32_16x16x32_bf16 v[112:115], v[192:195], v[210:213], v[112:115]
	v_mfma_f32_16x16x32_bf16 v[104:107], v[184:187], v[218:221], v[104:107]
	v_mfma_f32_16x16x32_bf16 v[96:99], v[192:195], v[218:221], v[96:99]
	v_mfma_f32_16x16x32_bf16 v[88:91], v[184:187], v[228:231], v[88:91]
	v_mfma_f32_16x16x32_bf16 v[80:83], v[192:195], v[228:231], v[80:83]
	v_mfma_f32_16x16x32_bf16 v[72:75], v[184:187], v[236:239], v[72:75]
	v_mfma_f32_16x16x32_bf16 v[64:67], v[192:195], v[236:239], v[64:67]
	v_mfma_f32_16x16x32_bf16 v[120:123], v[188:191], v[214:217], v[120:123]
	v_mfma_f32_16x16x32_bf16 v[112:115], v[196:199], v[214:217], v[112:115]
	v_mfma_f32_16x16x32_bf16 v[104:107], v[188:191], v[224:227], v[104:107]
	v_mfma_f32_16x16x32_bf16 v[96:99], v[196:199], v[224:227], v[96:99]
	v_mfma_f32_16x16x32_bf16 v[88:91], v[188:191], v[232:235], v[88:91]
	v_mfma_f32_16x16x32_bf16 v[80:83], v[196:199], v[232:235], v[80:83]
	v_mfma_f32_16x16x32_bf16 v[72:75], v[188:191], v[240:243], v[72:75]
	v_mfma_f32_16x16x32_bf16 v[64:67], v[196:199], v[240:243], v[64:67]
	s_setprio 0
	s_barrier
	s_add_i32 s86, s92, s67
	v_lshl_add_u64 v[142:143], v[142:143], 0, s[22:23]
	s_mov_b32 m0, s86
	ds_read_b128 v[210:213], v148 offset:49152
	ds_read_b128 v[214:217], v148 offset:50176
	ds_read_b128 v[218:221], v148 offset:51200
	ds_read_b128 v[224:227], v148 offset:52224
	ds_read_b128 v[228:231], v148 offset:53248
	ds_read_b128 v[232:235], v148 offset:54272
	ds_read_b128 v[236:239], v148 offset:55296
	ds_read_b128 v[240:243], v148 offset:56320
	global_load_lds_dwordx4 v[142:143], off
	s_add_i32 m0, s86, 0x2000
	s_add_u32 s62, s62, 0x40080
	v_lshl_add_u64 v[142:143], v[150:151], 0, s[22:23]
	s_addc_u32 s63, s63, 0
	s_add_i32 s86, s93, s67
	global_load_lds_dwordx4 v[142:143], off
	v_lshl_add_u64 v[142:143], s[62:63], 0, v[152:153]
	s_mov_b32 m0, s86
	s_nop 0
	global_load_lds_dwordx4 v[142:143], off
	v_lshl_add_u64 v[142:143], s[62:63], 0, v[128:129]
	s_add_i32 m0, s86, 0x2000
	s_nop 0
	global_load_lds_dwordx4 v[142:143], off
	v_lshl_add_u64 v[142:143], v[244:245], 0, s[22:23]
	s_mov_b32 m0, s77
	s_nop 0
	global_load_lds_dwordx4 v[142:143], off
	v_lshl_add_u64 v[142:143], v[246:247], 0, s[22:23]
	s_mov_b32 m0, s78
	s_nop 0
	global_load_lds_dwordx4 v[142:143], off
	s_waitcnt vmcnt(8)
	s_waitcnt lgkmcnt(0)
	s_barrier
	s_setprio 1
	s_waitcnt lgkmcnt(0)
	v_mfma_f32_16x16x32_bf16 v[60:63], v[138:141], v[210:213], v[60:63]
	v_mfma_f32_16x16x32_bf16 v[52:55], v[176:179], v[210:213], v[52:55]
	v_mfma_f32_16x16x32_bf16 v[44:47], v[138:141], v[218:221], v[44:47]
	v_mfma_f32_16x16x32_bf16 v[36:39], v[176:179], v[218:221], v[36:39]
	v_mfma_f32_16x16x32_bf16 v[28:31], v[138:141], v[228:231], v[28:31]
	v_mfma_f32_16x16x32_bf16 v[20:23], v[176:179], v[228:231], v[20:23]
	v_mfma_f32_16x16x32_bf16 v[12:15], v[138:141], v[236:239], v[12:15]
	v_mfma_f32_16x16x32_bf16 v[4:7], v[176:179], v[236:239], v[4:7]
	v_mfma_f32_16x16x32_bf16 v[60:63], v[172:175], v[214:217], v[60:63]
	v_mfma_f32_16x16x32_bf16 v[52:55], v[180:183], v[214:217], v[52:55]
	v_mfma_f32_16x16x32_bf16 v[44:47], v[172:175], v[224:227], v[44:47]
	v_mfma_f32_16x16x32_bf16 v[36:39], v[180:183], v[224:227], v[36:39]
	v_mfma_f32_16x16x32_bf16 v[28:31], v[172:175], v[232:235], v[28:31]
	v_mfma_f32_16x16x32_bf16 v[20:23], v[180:183], v[232:235], v[20:23]
	v_mfma_f32_16x16x32_bf16 v[12:15], v[172:175], v[240:243], v[12:15]
	v_mfma_f32_16x16x32_bf16 v[4:7], v[180:183], v[240:243], v[4:7]
	s_setprio 0
	s_setprio 1
	v_mfma_f32_16x16x32_bf16 v[56:59], v[184:187], v[210:213], v[56:59]
	v_mfma_f32_16x16x32_bf16 v[48:51], v[192:195], v[210:213], v[48:51]
	v_mfma_f32_16x16x32_bf16 v[40:43], v[184:187], v[218:221], v[40:43]
	v_mfma_f32_16x16x32_bf16 v[32:35], v[192:195], v[218:221], v[32:35]
	v_mfma_f32_16x16x32_bf16 v[24:27], v[184:187], v[228:231], v[24:27]
	v_mfma_f32_16x16x32_bf16 v[16:19], v[192:195], v[228:231], v[16:19]
	v_mfma_f32_16x16x32_bf16 v[8:11], v[184:187], v[236:239], v[8:11]
	v_mfma_f32_16x16x32_bf16 v[0:3], v[192:195], v[236:239], v[0:3]
	v_mfma_f32_16x16x32_bf16 v[56:59], v[188:191], v[214:217], v[56:59]
	v_mfma_f32_16x16x32_bf16 v[48:51], v[196:199], v[214:217], v[48:51]
	v_mfma_f32_16x16x32_bf16 v[40:43], v[188:191], v[224:227], v[40:43]
	v_mfma_f32_16x16x32_bf16 v[32:35], v[196:199], v[224:227], v[32:35]
	v_mfma_f32_16x16x32_bf16 v[24:27], v[188:191], v[232:235], v[24:27]
	v_mfma_f32_16x16x32_bf16 v[16:19], v[196:199], v[232:235], v[16:19]
	v_mfma_f32_16x16x32_bf16 v[8:11], v[188:191], v[240:243], v[8:11]
	v_mfma_f32_16x16x32_bf16 v[0:3], v[196:199], v[240:243], v[0:3]
	s_setprio 0
	s_barrier
	s_add_i32 s85, s85, 2
	s_add_u32 s89, s89, 0x100
	s_addc_u32 s84, s84, 0
	s_add_u32 s60, s60, 0x100
	s_addc_u32 s61, s61, 0
	s_cmp_gt_u32 s85, 13

.Lmy_up_e1:
	v_mul_f32_e32 v174, 0xbfb8aa3b, v172
	v_pk_mul_f32 v[176:177], v[126:127], v[174:175] op_sel_hi:[1,0]
	v_pk_mul_f32 v[178:179], v[124:125], v[174:175] op_sel_hi:[1,0]
	v_exp_f32_e32 v176, v176
	v_exp_f32_e32 v177, v177
	v_exp_f32_e32 v178, v178
	v_exp_f32_e32 v179, v179
	v_mul_f32_e32 v172, v172, v172
	v_pk_add_f32 v[176:177], v[176:177], 1.0 op_sel_hi:[1,0]
	v_pk_mul_f32 v[122:123], v[126:127], v[122:123]
	v_rcp_f32_e32 v176, v176
	v_rcp_f32_e32 v177, v177
	v_pk_add_f32 v[178:179], v[178:179], 1.0 op_sel_hi:[1,0]
	s_lshl_b32 s21, s81, 8
	v_rcp_f32_e32 v178, v178
	v_pk_mul_f32 v[124:125], v[172:173], v[176:177] op_sel_hi:[0,1]
	v_pk_mul_f32 v[176:177], v[118:119], v[174:175] op_sel_hi:[1,0]
	v_rcp_f32_e32 v179, v179
	v_pk_mul_f32 v[174:175], v[116:117], v[174:175] op_sel_hi:[1,0]
	v_exp_f32_e32 v176, v176
	v_exp_f32_e32 v177, v177
	v_exp_f32_e32 v174, v174
	v_exp_f32_e32 v175, v175
	v_pk_mul_f32 v[126:127], v[172:173], v[178:179] op_sel_hi:[0,1]
	v_pk_mul_f32 v[122:123], v[122:123], v[124:125]
	v_pk_add_f32 v[124:125], v[176:177], 1.0 op_sel_hi:[1,0]
	v_pk_mul_f32 v[120:121], v[120:121], v[126:127]
	v_pk_add_f32 v[126:127], v[174:175], 1.0 op_sel_hi:[1,0]
	v_rcp_f32_e32 v124, v124
	v_rcp_f32_e32 v125, v125
	v_rcp_f32_e32 v126, v126
	v_rcp_f32_e32 v127, v127
	v_pk_mul_f32 v[114:115], v[118:119], v[114:115]
	v_pk_mul_f32 v[112:113], v[116:117], v[112:113]
	v_pk_mul_f32 v[116:117], v[172:173], v[124:125] op_sel_hi:[0,1]
	s_add_i32 s21, s21, s76
	v_pk_mul_f32 v[118:119], v[172:173], v[126:127] op_sel_hi:[0,1]
	v_pk_mul_f32 v[114:115], v[114:115], v[116:117]
	v_cvt_pk_bf16_f32 v116, v120, v121
	v_cvt_pk_bf16_f32 v117, v122, v123
	v_mul_f32_e32 v122, 0xbfb8aa3b, v173
	s_ashr_i32 s60, s21, 12
	v_pk_mul_f32 v[112:113], v[112:113], v[118:119]
	v_pk_mul_f32 v[124:125], v[110:111], v[122:123] op_sel_hi:[1,0]
	v_pk_mul_f32 v[126:127], v[108:109], v[122:123] op_sel_hi:[1,0]
	v_or_b32_e32 v149, s21, v144
	v_lshl_or_b32 v150, s80, 7, v147
	s_ashr_i32 s61, s60, 31
	v_cvt_pk_bf16_f32 v118, v112, v113
	v_mov_b64_e32 v[112:113], s[56:57]
	v_exp_f32_e32 v126, v126
	v_exp_f32_e32 v124, v124
	v_exp_f32_e32 v125, v125
	v_exp_f32_e32 v127, v127
	v_ashrrev_i32_e32 v151, 31, v150
	v_cvt_pk_bf16_f32 v119, v114, v115
	v_mad_i64_i32 v[114:115], s[62:63], v149, s24, v[112:113]
	s_lshl_b64 s[60:61], s[60:61], 22
	v_lshl_add_u64 v[120:121], v[114:115], 0, s[60:61]
	v_lshlrev_b64 v[114:115], 1, v[150:151]
	v_lshl_add_u64 v[120:121], v[120:121], 0, v[114:115]
	global_store_dwordx4 v[120:121], v[116:119], off
	v_pk_add_f32 v[120:121], v[126:127], 1.0 op_sel_hi:[1,0]
	v_pk_mul_f32 v[106:107], v[110:111], v[106:107]
	v_pk_add_f32 v[118:119], v[124:125], 1.0 op_sel_hi:[1,0]
	v_rcp_f32_e32 v120, v120
	v_rcp_f32_e32 v118, v118
	v_rcp_f32_e32 v119, v119
	v_rcp_f32_e32 v121, v121
	v_mul_f32_e32 v116, v173, v173
	v_pk_mul_f32 v[104:105], v[108:109], v[104:105]
	v_pk_mul_f32 v[108:109], v[116:117], v[118:119] op_sel_hi:[0,1]
	v_pk_mul_f32 v[110:111], v[116:117], v[120:121] op_sel_hi:[0,1]
	v_pk_mul_f32 v[118:119], v[102:103], v[122:123] op_sel_hi:[1,0]
	v_pk_mul_f32 v[120:121], v[100:101], v[122:123] op_sel_hi:[1,0]
	v_exp_f32_e32 v118, v118
	v_exp_f32_e32 v120, v120
	v_exp_f32_e32 v119, v119
	v_exp_f32_e32 v121, v121
	v_pk_mul_f32 v[106:107], v[106:107], v[108:109]
	v_pk_mul_f32 v[104:105], v[104:105], v[110:111]
	v_pk_add_f32 v[108:109], v[118:119], 1.0 op_sel_hi:[1,0]
	v_pk_add_f32 v[110:111], v[120:121], 1.0 op_sel_hi:[1,0]
	v_rcp_f32_e32 v108, v108
	v_rcp_f32_e32 v110, v110
	v_rcp_f32_e32 v109, v109
	v_rcp_f32_e32 v111, v111
	v_pk_mul_f32 v[98:99], v[102:103], v[98:99]
	v_pk_mul_f32 v[96:97], v[100:101], v[96:97]
	v_pk_mul_f32 v[100:101], v[116:117], v[108:109] op_sel_hi:[0,1]
	v_pk_mul_f32 v[102:103], v[116:117], v[110:111] op_sel_hi:[0,1]
	v_pk_mul_f32 v[100:101], v[98:99], v[100:101]
	v_pk_mul_f32 v[98:99], v[96:97], v[102:103]
	v_or_b32_e32 v102, 16, v149
	v_cvt_pk_bf16_f32 v96, v104, v105
	v_cvt_pk_bf16_f32 v97, v106, v107
	v_cvt_pk_bf16_f32 v98, v98, v99
	v_cvt_pk_bf16_f32 v99, v100, v101
	v_mad_i64_i32 v[100:101], s[62:63], v102, s24, v[112:113]
	v_mul_f32_e32 v102, 0xbfb8aa3b, v142
	v_pk_mul_f32 v[104:105], v[94:95], v[102:103] op_sel_hi:[1,0]
	v_pk_mul_f32 v[106:107], v[92:93], v[102:103] op_sel_hi:[1,0]
	v_exp_f32_e32 v104, v104
	v_exp_f32_e32 v106, v106
	v_exp_f32_e32 v105, v105
	v_exp_f32_e32 v107, v107
	v_lshl_add_u64 v[100:101], v[100:101], 0, s[60:61]
	v_lshl_add_u64 v[100:101], v[100:101], 0, v[114:115]
	global_store_dwordx4 v[100:101], v[96:99], off
	v_pk_add_f32 v[100:101], v[106:107], 1.0 op_sel_hi:[1,0]
	v_pk_mul_f32 v[90:91], v[94:95], v[90:91]
	v_pk_add_f32 v[98:99], v[104:105], 1.0 op_sel_hi:[1,0]
	v_rcp_f32_e32 v100, v100
	v_rcp_f32_e32 v98, v98
	v_rcp_f32_e32 v99, v99
	v_rcp_f32_e32 v101, v101
	v_mul_f32_e32 v96, v142, v142
	v_pk_mul_f32 v[88:89], v[92:93], v[88:89]
	v_pk_mul_f32 v[92:93], v[96:97], v[98:99] op_sel_hi:[0,1]
	v_pk_mul_f32 v[94:95], v[96:97], v[100:101] op_sel_hi:[0,1]
	v_pk_mul_f32 v[98:99], v[86:87], v[102:103] op_sel_hi:[1,0]
	v_pk_mul_f32 v[100:101], v[84:85], v[102:103] op_sel_hi:[1,0]
	v_exp_f32_e32 v98, v98
	v_exp_f32_e32 v100, v100
	v_exp_f32_e32 v99, v99
	v_exp_f32_e32 v101, v101
	v_pk_mul_f32 v[90:91], v[90:91], v[92:93]
	v_pk_mul_f32 v[88:89], v[88:89], v[94:95]
	v_pk_add_f32 v[92:93], v[98:99], 1.0 op_sel_hi:[1,0]
	v_pk_add_f32 v[94:95], v[100:101], 1.0 op_sel_hi:[1,0]
	v_rcp_f32_e32 v92, v92
	v_rcp_f32_e32 v94, v94
	v_rcp_f32_e32 v93, v93
	v_rcp_f32_e32 v95, v95
	v_pk_mul_f32 v[82:83], v[86:87], v[82:83]
	v_pk_mul_f32 v[80:81], v[84:85], v[80:81]
	v_pk_mul_f32 v[84:85], v[96:97], v[92:93] op_sel_hi:[0,1]
	v_pk_mul_f32 v[86:87], v[96:97], v[94:95] op_sel_hi:[0,1]
	v_pk_mul_f32 v[84:85], v[82:83], v[84:85]
	v_pk_mul_f32 v[82:83], v[80:81], v[86:87]
	v_or_b32_e32 v86, 32, v149
	v_cvt_pk_bf16_f32 v80, v88, v89
	v_cvt_pk_bf16_f32 v81, v90, v91
	v_cvt_pk_bf16_f32 v82, v82, v83
	v_cvt_pk_bf16_f32 v83, v84, v85
	v_mad_i64_i32 v[84:85], s[62:63], v86, s24, v[112:113]
	v_mul_f32_e32 v86, 0xbfb8aa3b, v143
	v_pk_mul_f32 v[88:89], v[78:79], v[86:87] op_sel_hi:[1,0]
	v_pk_mul_f32 v[90:91], v[76:77], v[86:87] op_sel_hi:[1,0]
	v_exp_f32_e32 v88, v88
	v_exp_f32_e32 v90, v90
	v_exp_f32_e32 v89, v89
	v_exp_f32_e32 v91, v91
	v_lshl_add_u64 v[84:85], v[84:85], 0, s[60:61]
	v_lshl_add_u64 v[84:85], v[84:85], 0, v[114:115]
	global_store_dwordx4 v[84:85], v[80:83], off
	v_pk_add_f32 v[84:85], v[90:91], 1.0 op_sel_hi:[1,0]
	v_pk_mul_f32 v[74:75], v[78:79], v[74:75]
	v_pk_add_f32 v[82:83], v[88:89], 1.0 op_sel_hi:[1,0]
	v_rcp_f32_e32 v84, v84
	v_rcp_f32_e32 v82, v82
	v_rcp_f32_e32 v83, v83
	v_rcp_f32_e32 v85, v85
	v_mul_f32_e32 v80, v143, v143
	v_pk_mul_f32 v[72:73], v[76:77], v[72:73]
	v_pk_mul_f32 v[76:77], v[80:81], v[82:83] op_sel_hi:[0,1]
	v_pk_mul_f32 v[78:79], v[80:81], v[84:85] op_sel_hi:[0,1]
	v_pk_mul_f32 v[82:83], v[70:71], v[86:87] op_sel_hi:[1,0]
	v_pk_mul_f32 v[84:85], v[68:69], v[86:87] op_sel_hi:[1,0]
	v_exp_f32_e32 v82, v82
	v_exp_f32_e32 v84, v84
	v_exp_f32_e32 v83, v83
	v_exp_f32_e32 v85, v85
	v_pk_mul_f32 v[74:75], v[74:75], v[76:77]
	v_pk_mul_f32 v[72:73], v[72:73], v[78:79]
	v_pk_add_f32 v[76:77], v[82:83], 1.0 op_sel_hi:[1,0]
	v_pk_add_f32 v[78:79], v[84:85], 1.0 op_sel_hi:[1,0]
	v_rcp_f32_e32 v76, v76
	v_rcp_f32_e32 v78, v78
	v_rcp_f32_e32 v77, v77
	v_rcp_f32_e32 v79, v79
	v_pk_mul_f32 v[66:67], v[70:71], v[66:67]
	v_pk_mul_f32 v[64:65], v[68:69], v[64:65]
	v_pk_mul_f32 v[68:69], v[80:81], v[76:77] op_sel_hi:[0,1]
	v_pk_mul_f32 v[70:71], v[80:81], v[78:79] op_sel_hi:[0,1]
	v_pk_mul_f32 v[68:69], v[66:67], v[68:69]
	v_pk_mul_f32 v[66:67], v[64:65], v[70:71]
	v_or_b32_e32 v70, 48, v149
	v_cvt_pk_bf16_f32 v64, v72, v73
	v_cvt_pk_bf16_f32 v65, v74, v75
	v_cvt_pk_bf16_f32 v66, v66, v67
	v_cvt_pk_bf16_f32 v67, v68, v69
	v_mad_i64_i32 v[68:69], s[62:63], v70, s24, v[112:113]
	v_lshl_add_u64 v[68:69], v[68:69], 0, s[60:61]
	v_lshl_add_u64 v[68:69], v[68:69], 0, v[114:115]
	global_store_dwordx4 v[68:69], v[64:67], off
	v_add_u32_e32 v73, 0x80, v149
	v_mul_f32_e32 v72, v140, v140
	v_mul_f32_e32 v66, 0xbfb8aa3b, v140
	v_pk_mul_f32 v[68:69], v[62:63], v[66:67] op_sel_hi:[1,0]
	v_pk_mul_f32 v[70:71], v[60:61], v[66:67] op_sel_hi:[1,0]
	v_exp_f32_e32 v68, v68
	v_exp_f32_e32 v69, v69
	v_exp_f32_e32 v70, v70
	v_exp_f32_e32 v71, v71
	v_pk_mul_f32 v[56:57], v[60:61], v[56:57]
	v_pk_add_f32 v[68:69], v[68:69], 1.0 op_sel_hi:[1,0]
	v_pk_mul_f32 v[58:59], v[62:63], v[58:59]
	v_rcp_f32_e32 v68, v68
	v_rcp_f32_e32 v69, v69
	v_pk_add_f32 v[70:71], v[70:71], 1.0 op_sel_hi:[1,0]
	v_pk_mul_f32 v[50:51], v[54:55], v[50:51]
	v_rcp_f32_e32 v70, v70
	v_pk_mul_f32 v[60:61], v[72:73], v[68:69] op_sel_hi:[0,1]
	v_pk_mul_f32 v[68:69], v[54:55], v[66:67] op_sel_hi:[1,0]
	v_rcp_f32_e32 v71, v71
	v_pk_mul_f32 v[66:67], v[52:53], v[66:67] op_sel_hi:[1,0]
	v_exp_f32_e32 v68, v68
	v_exp_f32_e32 v69, v69
	v_exp_f32_e32 v66, v66
	v_exp_f32_e32 v67, v67
	v_pk_mul_f32 v[62:63], v[72:73], v[70:71] op_sel_hi:[0,1]
	v_pk_mul_f32 v[58:59], v[58:59], v[60:61]
	v_pk_add_f32 v[60:61], v[68:69], 1.0 op_sel_hi:[1,0]
	v_pk_mul_f32 v[56:57], v[56:57], v[62:63]
	v_pk_add_f32 v[62:63], v[66:67], 1.0 op_sel_hi:[1,0]
	v_rcp_f32_e32 v60, v60
	v_rcp_f32_e32 v61, v61
	v_rcp_f32_e32 v62, v62
	v_rcp_f32_e32 v63, v63
	v_pk_mul_f32 v[48:49], v[52:53], v[48:49]
	v_pk_mul_f32 v[52:53], v[72:73], v[60:61] op_sel_hi:[0,1]
	v_pk_mul_f32 v[60:61], v[50:51], v[52:53]
	v_pk_mul_f32 v[54:55], v[72:73], v[62:63] op_sel_hi:[0,1]
	v_cvt_pk_bf16_f32 v50, v56, v57
	v_mul_f32_e32 v56, 0xbfb8aa3b, v141
	v_ashrrev_i32_e32 v64, 12, v73
	v_pk_mul_f32 v[48:49], v[48:49], v[54:55]
	v_cvt_pk_bf16_f32 v51, v58, v59
	v_pk_mul_f32 v[58:59], v[46:47], v[56:57] op_sel_hi:[1,0]
	v_cvt_pk_bf16_f32 v52, v48, v49
	v_cvt_pk_bf16_f32 v53, v60, v61
	v_pk_mul_f32 v[60:61], v[44:45], v[56:57] op_sel_hi:[1,0]
	v_ashrrev_i32_e32 v65, 31, v64
	v_exp_f32_e32 v60, v60
	v_exp_f32_e32 v58, v58
	v_exp_f32_e32 v59, v59
	v_exp_f32_e32 v61, v61
	v_mad_i64_i32 v[54:55], s[60:61], v73, s24, v[112:113]
	v_lshlrev_b64 v[48:49], 22, v[64:65]
	v_lshl_add_u64 v[54:55], v[54:55], 0, v[48:49]
	v_lshl_add_u64 v[54:55], v[54:55], 0, v[114:115]
	global_store_dwordx4 v[54:55], v[50:53], off
	v_pk_add_f32 v[54:55], v[60:61], 1.0 op_sel_hi:[1,0]
	v_pk_mul_f32 v[42:43], v[46:47], v[42:43]
	v_pk_add_f32 v[52:53], v[58:59], 1.0 op_sel_hi:[1,0]
	v_rcp_f32_e32 v54, v54
	v_rcp_f32_e32 v52, v52
	v_rcp_f32_e32 v53, v53
	v_rcp_f32_e32 v55, v55
	v_mul_f32_e32 v50, v141, v141
	v_pk_mul_f32 v[40:41], v[44:45], v[40:41]
	v_pk_mul_f32 v[44:45], v[50:51], v[52:53] op_sel_hi:[0,1]
	v_pk_mul_f32 v[46:47], v[50:51], v[54:55] op_sel_hi:[0,1]
	v_pk_mul_f32 v[52:53], v[38:39], v[56:57] op_sel_hi:[1,0]
	v_pk_mul_f32 v[54:55], v[36:37], v[56:57] op_sel_hi:[1,0]
	v_exp_f32_e32 v52, v52
	v_exp_f32_e32 v54, v54
	v_exp_f32_e32 v53, v53
	v_exp_f32_e32 v55, v55
	v_pk_mul_f32 v[42:43], v[42:43], v[44:45]
	v_pk_mul_f32 v[40:41], v[40:41], v[46:47]
	v_pk_add_f32 v[44:45], v[52:53], 1.0 op_sel_hi:[1,0]
	v_pk_add_f32 v[46:47], v[54:55], 1.0 op_sel_hi:[1,0]
	v_rcp_f32_e32 v44, v44
	v_rcp_f32_e32 v46, v46
	v_rcp_f32_e32 v45, v45
	v_rcp_f32_e32 v47, v47
	v_pk_mul_f32 v[34:35], v[38:39], v[34:35]
	v_pk_mul_f32 v[32:33], v[36:37], v[32:33]
	v_pk_mul_f32 v[36:37], v[50:51], v[44:45] op_sel_hi:[0,1]
	v_pk_mul_f32 v[38:39], v[50:51], v[46:47] op_sel_hi:[0,1]
	v_pk_mul_f32 v[36:37], v[34:35], v[36:37]
	v_pk_mul_f32 v[34:35], v[32:33], v[38:39]
	v_add_u32_e32 v38, 0x90, v149
	v_cvt_pk_bf16_f32 v32, v40, v41
	v_cvt_pk_bf16_f32 v33, v42, v43
	v_cvt_pk_bf16_f32 v34, v34, v35
	v_cvt_pk_bf16_f32 v35, v36, v37
	v_mad_i64_i32 v[36:37], s[60:61], v38, s24, v[112:113]
	v_mul_f32_e32 v38, 0xbfb8aa3b, v138
	v_pk_mul_f32 v[40:41], v[30:31], v[38:39] op_sel_hi:[1,0]
	v_pk_mul_f32 v[42:43], v[28:29], v[38:39] op_sel_hi:[1,0]
	v_exp_f32_e32 v40, v40
	v_exp_f32_e32 v42, v42
	v_exp_f32_e32 v41, v41
	v_exp_f32_e32 v43, v43
	v_lshl_add_u64 v[36:37], v[36:37], 0, v[48:49]
	v_lshl_add_u64 v[36:37], v[36:37], 0, v[114:115]
	global_store_dwordx4 v[36:37], v[32:35], off
	v_pk_add_f32 v[36:37], v[42:43], 1.0 op_sel_hi:[1,0]
	v_pk_mul_f32 v[26:27], v[30:31], v[26:27]
	v_pk_add_f32 v[34:35], v[40:41], 1.0 op_sel_hi:[1,0]
	v_rcp_f32_e32 v36, v36
	v_rcp_f32_e32 v34, v34
	v_rcp_f32_e32 v35, v35
	v_rcp_f32_e32 v37, v37
	v_mul_f32_e32 v32, v138, v138
	v_pk_mul_f32 v[24:25], v[28:29], v[24:25]
	v_pk_mul_f32 v[28:29], v[32:33], v[34:35] op_sel_hi:[0,1]
	v_pk_mul_f32 v[30:31], v[32:33], v[36:37] op_sel_hi:[0,1]
	v_pk_mul_f32 v[34:35], v[22:23], v[38:39] op_sel_hi:[1,0]
	v_pk_mul_f32 v[36:37], v[20:21], v[38:39] op_sel_hi:[1,0]
	v_exp_f32_e32 v34, v34
	v_exp_f32_e32 v36, v36
	v_exp_f32_e32 v35, v35
	v_exp_f32_e32 v37, v37
	v_pk_mul_f32 v[26:27], v[26:27], v[28:29]
	v_pk_mul_f32 v[24:25], v[24:25], v[30:31]
	v_pk_add_f32 v[28:29], v[34:35], 1.0 op_sel_hi:[1,0]
	v_pk_add_f32 v[30:31], v[36:37], 1.0 op_sel_hi:[1,0]
	v_rcp_f32_e32 v28, v28
	v_rcp_f32_e32 v30, v30
	v_rcp_f32_e32 v29, v29
	v_rcp_f32_e32 v31, v31
	v_pk_mul_f32 v[18:19], v[22:23], v[18:19]
	v_pk_mul_f32 v[16:17], v[20:21], v[16:17]
	v_pk_mul_f32 v[20:21], v[32:33], v[28:29] op_sel_hi:[0,1]
	v_pk_mul_f32 v[22:23], v[32:33], v[30:31] op_sel_hi:[0,1]
	v_pk_mul_f32 v[20:21], v[18:19], v[20:21]
	v_pk_mul_f32 v[18:19], v[16:17], v[22:23]
	v_add_u32_e32 v22, 0xa0, v149
	v_cvt_pk_bf16_f32 v16, v24, v25
	v_cvt_pk_bf16_f32 v17, v26, v27
	v_cvt_pk_bf16_f32 v18, v18, v19
	v_cvt_pk_bf16_f32 v19, v20, v21
	v_mad_i64_i32 v[20:21], s[60:61], v22, s24, v[112:113]
	v_lshl_add_u64 v[20:21], v[20:21], 0, v[48:49]
	v_lshl_add_u64 v[20:21], v[20:21], 0, v[114:115]
	global_store_dwordx4 v[20:21], v[16:19], off
	v_add_u32_e32 v22, 0xb0, v149
	v_mad_i64_i32 v[28:29], s[60:61], v22, s24, v[112:113]
	v_lshl_add_u64 v[28:29], v[28:29], 0, v[48:49]
	v_lshl_add_u64 v[28:29], v[28:29], 0, v[114:115]
	v_mov_b32_e32 v30, v139
	s_andn2_b64 vcc, exec, s[44:45]
	s_mov_b64 s[44:45], -1
	s_cbranch_vccnz .Lmy_up_g7_inline
	s_andn2_b64 vcc, exec, s[16:17]
	s_cbranch_vccnz .LBB0_175
	s_barrier
	s_branch .LBB0_175
.Lmy_up_g7_inline:
	v_mul_f32_e32 v22, 0xbfb8aa3b, v30
	v_pk_mul_f32 v[24:25], v[14:15], v[22:23] op_sel_hi:[1,0]
	v_pk_mul_f32 v[26:27], v[12:13], v[22:23] op_sel_hi:[1,0]
	v_exp_f32_e32 v24, v24
	v_exp_f32_e32 v26, v26
	v_exp_f32_e32 v25, v25
	v_exp_f32_e32 v27, v27
	s_nop 0
	v_pk_add_f32 v[20:21], v[26:27], 1.0 op_sel_hi:[1,0]
	v_pk_mul_f32 v[10:11], v[14:15], v[10:11]
	v_pk_add_f32 v[18:19], v[24:25], 1.0 op_sel_hi:[1,0]
	v_rcp_f32_e32 v20, v20
	v_rcp_f32_e32 v18, v18
	v_rcp_f32_e32 v19, v19
	v_rcp_f32_e32 v21, v21
	v_mul_f32_e32 v16, v30, v30
	v_pk_mul_f32 v[8:9], v[12:13], v[8:9]
	v_pk_mul_f32 v[12:13], v[16:17], v[18:19] op_sel_hi:[0,1]
	v_pk_mul_f32 v[14:15], v[16:17], v[20:21] op_sel_hi:[0,1]
	v_pk_mul_f32 v[18:19], v[6:7], v[22:23] op_sel_hi:[1,0]
	v_pk_mul_f32 v[20:21], v[4:5], v[22:23] op_sel_hi:[1,0]
	v_exp_f32_e32 v18, v18
	v_exp_f32_e32 v20, v20
	v_exp_f32_e32 v19, v19
	v_exp_f32_e32 v21, v21
	v_pk_mul_f32 v[10:11], v[10:11], v[12:13]
	v_pk_mul_f32 v[8:9], v[8:9], v[14:15]
	v_pk_add_f32 v[12:13], v[18:19], 1.0 op_sel_hi:[1,0]
	v_pk_add_f32 v[14:15], v[20:21], 1.0 op_sel_hi:[1,0]
	v_rcp_f32_e32 v12, v12
	v_rcp_f32_e32 v14, v14
	v_rcp_f32_e32 v13, v13
	v_rcp_f32_e32 v15, v15
	v_pk_mul_f32 v[2:3], v[6:7], v[2:3]
	v_pk_mul_f32 v[0:1], v[4:5], v[0:1]
	v_pk_mul_f32 v[4:5], v[16:17], v[12:13] op_sel_hi:[0,1]
	v_pk_mul_f32 v[6:7], v[16:17], v[14:15] op_sel_hi:[0,1]
	v_pk_mul_f32 v[4:5], v[2:3], v[4:5]
	v_pk_mul_f32 v[2:3], v[0:1], v[6:7]
	v_cvt_pk_bf16_f32 v0, v8, v9
	v_cvt_pk_bf16_f32 v1, v10, v11
	v_cvt_pk_bf16_f32 v2, v2, v3
	v_cvt_pk_bf16_f32 v3, v4, v5
	global_store_dwordx4 v[28:29], v[0:3], off
	s_branch .LBB0_176
